# NSA_QB table: rounds 0-2 prefix-balanced across all slots, sample compensation entirely in last round (230/278)
# speedup vs baseline: 1.0230x; 1.0166x over previous
_ZL6NSA_QB:
	.byte	127, 48, 47, 8, 126, 49, 46, 9, 125, 50, 45, 10, 124, 51, 44, 11, 123, 52, 43, 12, 122, 53, 42, 13, 121, 54, 41, 14, 120, 55, 40, 15, 119, 72, 39, 0, 118, 73, 38, 1, 117, 74, 37, 2, 116, 75, 36, 3, 115, 76, 35, 4, 114, 77, 34, 5, 113, 78, 33, 6, 112, 79, 32, 7, 111, 80, 31, 56, 110, 81, 30, 57, 109, 82, 29, 58, 108, 83, 28, 59, 107, 84, 27, 60, 106, 85, 26, 61, 105, 86, 25, 62, 104, 87, 24, 63, 103, 88, 23, 64, 102, 89, 22, 65, 101, 90, 21, 66, 100, 91, 20, 67, 99, 92, 19, 68, 98, 93, 18, 69, 97, 94, 17, 70, 96, 95, 16, 71
	.size	_ZL6NSA_QB, 128

	.type	__hip_cuid_aaa9f4bcd633d1df,@object
